# speedup vs baseline: 1.0160x; 1.0012x over previous
; #define PG8_STAGE(bufoff, gbase, voff) do { _Pragma("unroll") for (int _i = 0; _i < 2; ++_i) \
;         __builtin_amdgcn_global_load_lds((const unsigned*)((const char*)(gbase) + (voff)[_i]), (LAS unsigned*)(lds + (bufoff) + ldsw + _i * 8192), 16, 0, 0); } while (0)
; #define PG8_LDA(dst, b, h) do { _Pragma("unroll") for (int m = 0; m < 4; ++m) _Pragma("unroll") for (int k = 0; k < 2; ++k) dst[m][k] = *(const LAS bf16x8*)(lds + PG8_SA(b, h) + aoff + m * 2048 + k * 1024); } while (0)
; #define PG8_LDB(dst, b, h) do { _Pragma("unroll") for (int n = 0; n < 2; ++n) _Pragma("unroll") for (int k = 0; k < 2; ++k) dst[n][k] = *(const LAS bf16x8*)(lds + PG8_SB(b, h) + boff + n * 2048 + k * 1024); } while (0)
; template <class Epi, class Sched>
; __device__ __forceinline__ void gemm_phase(LAS unsigned char* lds, const Gemm g, const Sched& S, const Epi& E, const int tid) {
;     ...
;         for (int t = 0; t < nt; t += 2) {
;             const bool last = (t == nt - 2);
;             const char* a1 = cA + (size_t)(t + 1) * kstepA;
;             const char* a2 = last ? nA : cA + (size_t)(t + 2) * kstepA; const char* b2 = last ? nB : cB + (size_t)(t + 2) * kstep;
;             const char* a3 = a2 + kstepA; const char* b3 = b2 + kstep;
;             if constexpr (Epi::HAS_MID) { if (t == g.tmid) E.mid(acc, cur, ui, wr, wc, fr, fq); }
;             PG8_LDB(B0, 0, 0); PG8_LDB(B1, 0, 1); PG8_SCHED; PG8_LDA(At, 0, 0); PG8_STAGE(PG8_SA(1, 1), a1 + hstepA, voffA);
;             PG8_WAIT_V(8); PG8_WAIT_L(0); PG8_BAR; PG8_MMA(0, 0, At, B0); PG8_MMA(0, 1, At, B1); PG8_BAR; PG8_SCHED;
;             PG8_LDA(At, 0, 1); PG8_STAGE(PG8_SB(0, 0), b2, voffB); PG8_STAGE(PG8_SB(0, 1), b2 + hstepB, voffB); PG8_STAGE(PG8_SA(0, 0), a2, voffA);
;             PG8_WAIT_V(8); PG8_WAIT_L(0); PG8_BAR; PG8_MMA(1, 0, At, B0); PG8_MMA(1, 1, At, B1); PG8_BAR; PG8_SCHED;
;             PG8_LDB(B0, 1, 0); PG8_LDB(B1, 1, 1); PG8_SCHED; PG8_LDA(At, 1, 0); PG8_STAGE(PG8_SA(0, 1), a2 + hstepA, voffA);
;             PG8_WAIT_V(8); PG8_WAIT_L(0); PG8_BAR; PG8_MMA(0, 0, At, B0); PG8_MMA(0, 1, At, B1); PG8_BAR; PG8_SCHED;
;             PG8_LDA(At, 1, 1); PG8_STAGE(PG8_SB(1, 0), b3, voffB); PG8_STAGE(PG8_SB(1, 1), b3 + hstepB, voffB); PG8_STAGE(PG8_SA(1, 0), a3, voffA);
;             PG8_WAIT_V(8); PG8_WAIT_L(0); PG8_BAR; PG8_MMA(1, 0, At, B0); PG8_MMA(1, 1, At, B1); PG8_BAR; PG8_SCHED;
.LBB0_285:
	ds_read_b128 v[128:131], v173
	ds_read_b128 v[158:161], v173 offset:1024
	ds_read_b128 v[178:181], v173 offset:2048
	ds_read_b128 v[182:185], v173 offset:3072
	ds_read_b128 v[186:189], v174
	ds_read_b128 v[190:193], v174 offset:1024
	ds_read_b128 v[194:197], v174 offset:2048
	ds_read_b128 v[198:201], v174 offset:3072
	s_add_u32 s16, s8, 0xfff80080
	s_addc_u32 s17, s9, -1
	s_cmp_eq_u32 s48, 28
	s_cselect_b32 s31, s7, s17
	s_cselect_b32 s30, s18, s16
	s_cselect_b32 s27, s19, s39
	s_cselect_b32 s26, s29, s38
	v_lshl_add_u64 v[162:163], s[8:9], 0, v[150:151]
	s_add_i32 m0, s41, 0xc000
	ds_read_b128 v[202:205], v175
	ds_read_b128 v[206:209], v175 offset:1024
	ds_read_b128 v[210:213], v175 offset:2048
	ds_read_b128 v[214:217], v175 offset:3072
	ds_read_b128 v[218:221], v175 offset:4096
	ds_read_b128 v[222:225], v175 offset:5120
	ds_read_b128 v[226:229], v175 offset:6144
	ds_read_b128 v[230:233], v175 offset:7168
	global_load_lds_dwordx4 v[162:163], off
	v_lshl_add_u64 v[162:163], s[8:9], 0, v[152:153]
	s_add_i32 m0, s41, 0xe000
	s_nop 0
	global_load_lds_dwordx4 v[162:163], off
	s_waitcnt vmcnt(8)
	s_waitcnt lgkmcnt(0)
	s_barrier
	s_setprio 1
	s_waitcnt lgkmcnt(0)
	v_mfma_f32_16x16x32_bf16 v[124:127], v[128:131], v[202:205], v[124:127]
	v_mfma_f32_16x16x32_bf16 v[120:123], v[178:181], v[202:205], v[120:123]
	v_mfma_f32_16x16x32_bf16 v[108:111], v[128:131], v[210:213], v[108:111]
	v_mfma_f32_16x16x32_bf16 v[104:107], v[178:181], v[210:213], v[104:107]
	v_mfma_f32_16x16x32_bf16 v[92:95], v[128:131], v[218:221], v[92:95]
	v_mfma_f32_16x16x32_bf16 v[88:91], v[178:181], v[218:221], v[88:91]
	v_mfma_f32_16x16x32_bf16 v[76:79], v[128:131], v[226:229], v[76:79]
	v_mfma_f32_16x16x32_bf16 v[72:75], v[178:181], v[226:229], v[72:75]
	v_mfma_f32_16x16x32_bf16 v[124:127], v[158:161], v[206:209], v[124:127]
	v_mfma_f32_16x16x32_bf16 v[120:123], v[182:185], v[206:209], v[120:123]
	v_mfma_f32_16x16x32_bf16 v[108:111], v[158:161], v[214:217], v[108:111]
	v_mfma_f32_16x16x32_bf16 v[104:107], v[182:185], v[214:217], v[104:107]
	v_mfma_f32_16x16x32_bf16 v[92:95], v[158:161], v[222:225], v[92:95]
	v_mfma_f32_16x16x32_bf16 v[88:91], v[182:185], v[222:225], v[88:91]
	v_mfma_f32_16x16x32_bf16 v[76:79], v[158:161], v[230:233], v[76:79]
	v_mfma_f32_16x16x32_bf16 v[72:75], v[182:185], v[230:233], v[72:75]
	s_setprio 0
	s_setprio 1
	s_cmp_eq_u32 s52, 12
	s_cbranch_scc1 .Lp2_skip0
	v_mfma_f32_16x16x32_bf16 v[116:119], v[186:189], v[202:205], v[116:119]
	v_mfma_f32_16x16x32_bf16 v[112:115], v[194:197], v[202:205], v[112:115]
	v_mfma_f32_16x16x32_bf16 v[100:103], v[186:189], v[210:213], v[100:103]
	v_mfma_f32_16x16x32_bf16 v[96:99], v[194:197], v[210:213], v[96:99]
	v_mfma_f32_16x16x32_bf16 v[84:87], v[186:189], v[218:221], v[84:87]
	v_mfma_f32_16x16x32_bf16 v[80:83], v[194:197], v[218:221], v[80:83]
	v_mfma_f32_16x16x32_bf16 v[68:71], v[186:189], v[226:229], v[68:71]
	v_mfma_f32_16x16x32_bf16 v[64:67], v[194:197], v[226:229], v[64:67]
	v_mfma_f32_16x16x32_bf16 v[116:119], v[190:193], v[206:209], v[116:119]
	v_mfma_f32_16x16x32_bf16 v[112:115], v[198:201], v[206:209], v[112:115]
	v_mfma_f32_16x16x32_bf16 v[100:103], v[190:193], v[214:217], v[100:103]
	v_mfma_f32_16x16x32_bf16 v[96:99], v[198:201], v[214:217], v[96:99]
	v_mfma_f32_16x16x32_bf16 v[84:87], v[190:193], v[222:225], v[84:87]
	v_mfma_f32_16x16x32_bf16 v[80:83], v[198:201], v[222:225], v[80:83]
	v_mfma_f32_16x16x32_bf16 v[68:71], v[190:193], v[230:233], v[68:71]
	v_mfma_f32_16x16x32_bf16 v[64:67], v[198:201], v[230:233], v[64:67]
.Lp2_skip0:
	s_setprio 0
	s_barrier
	s_add_i32 s16, s51, s33
	v_lshl_add_u64 v[162:163], s[26:27], 0, v[134:135]
	s_mov_b32 m0, s16
	ds_read_b128 v[202:205], v175 offset:16384
	ds_read_b128 v[206:209], v175 offset:17408
	ds_read_b128 v[210:213], v175 offset:18432
	ds_read_b128 v[214:217], v175 offset:19456
	ds_read_b128 v[218:221], v175 offset:20480
	ds_read_b128 v[222:225], v175 offset:21504
	ds_read_b128 v[226:229], v175 offset:22528
	ds_read_b128 v[230:233], v175 offset:23552
	global_load_lds_dwordx4 v[162:163], off
	s_add_i32 m0, s16, 0x2000
	s_add_u32 s54, s26, 0x80000
	v_lshl_add_u64 v[234:235], s[26:27], 0, v[138:139]
	s_addc_u32 s55, s27, 0
	s_add_i32 s16, s20, s33
	global_load_lds_dwordx4 v[234:235], off
	v_lshl_add_u64 v[236:237], s[54:55], 0, v[134:135]
	s_mov_b32 m0, s16
	v_lshl_add_u64 v[238:239], s[30:31], 0, v[136:137]
	global_load_lds_dwordx4 v[236:237], off
	v_lshl_add_u64 v[236:237], s[54:55], 0, v[138:139]
	s_add_i32 m0, s16, 0x2000
	s_nop 0
	global_load_lds_dwordx4 v[236:237], off
	v_lshl_add_u64 v[236:237], s[30:31], 0, v[132:133]
	s_mov_b32 m0, s41
	s_nop 0
	global_load_lds_dwordx4 v[236:237], off
	s_mov_b32 m0, s43
	s_nop 0
	global_load_lds_dwordx4 v[238:239], off
	s_waitcnt vmcnt(8)
	s_waitcnt lgkmcnt(0)
	s_barrier
	s_setprio 1
	s_waitcnt lgkmcnt(0)
	v_mfma_f32_16x16x32_bf16 v[60:63], v[128:131], v[202:205], v[60:63]
	v_mfma_f32_16x16x32_bf16 v[56:59], v[178:181], v[202:205], v[56:59]
	v_mfma_f32_16x16x32_bf16 v[44:47], v[128:131], v[210:213], v[44:47]
	v_mfma_f32_16x16x32_bf16 v[40:43], v[178:181], v[210:213], v[40:43]
	v_mfma_f32_16x16x32_bf16 v[28:31], v[128:131], v[218:221], v[28:31]
	v_mfma_f32_16x16x32_bf16 v[24:27], v[178:181], v[218:221], v[24:27]
	v_mfma_f32_16x16x32_bf16 v[12:15], v[128:131], v[226:229], v[12:15]
	v_mfma_f32_16x16x32_bf16 v[8:11], v[178:181], v[226:229], v[8:11]
	v_mfma_f32_16x16x32_bf16 v[60:63], v[158:161], v[206:209], v[60:63]
	v_mfma_f32_16x16x32_bf16 v[56:59], v[182:185], v[206:209], v[56:59]
	v_mfma_f32_16x16x32_bf16 v[44:47], v[158:161], v[214:217], v[44:47]
	v_mfma_f32_16x16x32_bf16 v[40:43], v[182:185], v[214:217], v[40:43]
	v_mfma_f32_16x16x32_bf16 v[28:31], v[158:161], v[222:225], v[28:31]
	v_mfma_f32_16x16x32_bf16 v[24:27], v[182:185], v[222:225], v[24:27]
	v_mfma_f32_16x16x32_bf16 v[12:15], v[158:161], v[230:233], v[12:15]
	v_mfma_f32_16x16x32_bf16 v[8:11], v[182:185], v[230:233], v[8:11]
	s_setprio 0
	s_setprio 1
	s_cmp_eq_u32 s52, 12
	s_cbranch_scc1 .Lp2_skip1
; #define PG8_STAGE(bufoff, gbase, voff) do { _Pragma("unroll") for (int _i = 0; _i < 2; ++_i) \
;         __builtin_amdgcn_global_load_lds((const unsigned*)((const char*)(gbase) + (voff)[_i]), (LAS unsigned*)(lds + (bufoff) + ldsw + _i * 8192), 16, 0, 0); } while (0)
; #define PG8_LDA(dst, b, h) do { _Pragma("unroll") for (int m = 0; m < 4; ++m) _Pragma("unroll") for (int k = 0; k < 2; ++k) dst[m][k] = *(const LAS bf16x8*)(lds + PG8_SA(b, h) + aoff + m * 2048 + k * 1024); } while (0)
; #define PG8_LDB(dst, b, h) do { _Pragma("unroll") for (int n = 0; n < 2; ++n) _Pragma("unroll") for (int k = 0; k < 2; ++k) dst[n][k] = *(const LAS bf16x8*)(lds + PG8_SB(b, h) + boff + n * 2048 + k * 1024); } while (0)
; #define PG8_MMA(ai, bj, At, Bt) do { __builtin_amdgcn_s_setprio(1); _Pragma("unroll") for (int m = 0; m < 4; ++m) _Pragma("unroll") for (int n = 0; n < 2; ++n) _Pragma("unroll") for (int k = 0; k < 2; ++k) \
;         acc[ai][bj][m][n] = __builtin_amdgcn_mfma_f32_16x16x32_bf16(Bt[n][k], At[m][k], acc[ai][bj][m][n], 0, 0, 0); __builtin_amdgcn_s_setprio(0); } while (0)
; #define PG8_WAIT_V(n) asm volatile("s_waitcnt vmcnt(" #n ")" ::: "memory")
; template <class Epi, class Sched>
; __device__ __forceinline__ void gemm_phase(LAS unsigned char* lds, const Gemm g, const Sched& S, const Epi& E, const int tid) {
;     ...
;             PG8_LDB(B0, 0, 0); PG8_LDB(B1, 0, 1); PG8_SCHED; PG8_LDA(At, 0, 0); PG8_STAGE(PG8_SA(1, 1), a1 + hstepA, voffA);
;             PG8_WAIT_V(8); PG8_WAIT_L(0); PG8_BAR; PG8_MMA(0, 0, At, B0); PG8_MMA(0, 1, At, B1); PG8_BAR; PG8_SCHED;
;             PG8_LDA(At, 0, 1); PG8_STAGE(PG8_SB(0, 0), b2, voffB); PG8_STAGE(PG8_SB(0, 1), b2 + hstepB, voffB); PG8_STAGE(PG8_SA(0, 0), a2, voffA);
;             PG8_WAIT_V(8); PG8_WAIT_L(0); PG8_BAR; PG8_MMA(1, 0, At, B0); PG8_MMA(1, 1, At, B1); PG8_BAR; PG8_SCHED;
;             PG8_LDB(B0, 1, 0); PG8_LDB(B1, 1, 1); PG8_SCHED; PG8_LDA(At, 1, 0); PG8_STAGE(PG8_SA(0, 1), a2 + hstepA, voffA);
;             PG8_WAIT_V(8); PG8_WAIT_L(0); PG8_BAR; PG8_MMA(0, 0, At, B0); PG8_MMA(0, 1, At, B1); PG8_BAR; PG8_SCHED;
;             PG8_LDA(At, 1, 1); PG8_STAGE(PG8_SB(1, 0), b3, voffB); PG8_STAGE(PG8_SB(1, 1), b3 + hstepB, voffB); PG8_STAGE(PG8_SA(1, 0), a3, voffA);
;             PG8_WAIT_V(8); PG8_WAIT_L(0); PG8_BAR; PG8_MMA(1, 0, At, B0); PG8_MMA(1, 1, At, B1); PG8_BAR; PG8_SCHED;
	v_mfma_f32_16x16x32_bf16 v[52:55], v[186:189], v[202:205], v[52:55]
	v_mfma_f32_16x16x32_bf16 v[48:51], v[194:197], v[202:205], v[48:51]
	v_mfma_f32_16x16x32_bf16 v[36:39], v[186:189], v[210:213], v[36:39]
	v_mfma_f32_16x16x32_bf16 v[32:35], v[194:197], v[210:213], v[32:35]
	v_mfma_f32_16x16x32_bf16 v[20:23], v[186:189], v[218:221], v[20:23]
	v_mfma_f32_16x16x32_bf16 v[16:19], v[194:197], v[218:221], v[16:19]
	v_mfma_f32_16x16x32_bf16 v[4:7], v[186:189], v[226:229], v[4:7]
	v_mfma_f32_16x16x32_bf16 v[0:3], v[194:197], v[226:229], v[0:3]
	v_mfma_f32_16x16x32_bf16 v[52:55], v[190:193], v[206:209], v[52:55]
	v_mfma_f32_16x16x32_bf16 v[48:51], v[198:201], v[206:209], v[48:51]
	v_mfma_f32_16x16x32_bf16 v[36:39], v[190:193], v[214:217], v[36:39]
	v_mfma_f32_16x16x32_bf16 v[32:35], v[198:201], v[214:217], v[32:35]
	v_mfma_f32_16x16x32_bf16 v[20:23], v[190:193], v[222:225], v[20:23]
	v_mfma_f32_16x16x32_bf16 v[16:19], v[198:201], v[222:225], v[16:19]
	v_mfma_f32_16x16x32_bf16 v[4:7], v[190:193], v[230:233], v[4:7]
	v_mfma_f32_16x16x32_bf16 v[0:3], v[198:201], v[230:233], v[0:3]
.Lp2_skip1:
	s_setprio 0
	s_barrier
	s_add_i32 s16, 0, 0x18000
	v_add_u32_e32 v140, s16, v164
	s_add_i32 s17, 0, 0x1c000
	ds_read_b128 v[128:131], v140
	ds_read_b128 v[158:161], v140 offset:1024
	ds_read_b128 v[178:181], v140 offset:2048
	ds_read_b128 v[182:185], v140 offset:3072
	v_add_u32_e32 v140, s17, v164
	ds_read_b128 v[186:189], v140
	ds_read_b128 v[190:193], v140 offset:1024
	ds_read_b128 v[194:197], v140 offset:2048
	ds_read_b128 v[198:201], v140 offset:3072
	s_add_u32 s30, s30, 0x80000
	s_addc_u32 s31, s31, 0
	s_mov_b32 m0, s53
	v_lshl_add_u64 v[240:241], s[30:31], 0, v[132:133]
	ds_read_b128 v[202:205], v175 offset:32768
	ds_read_b128 v[206:209], v175 offset:33792
	ds_read_b128 v[210:213], v175 offset:34816
	ds_read_b128 v[214:217], v175 offset:35840
	ds_read_b128 v[218:221], v175 offset:36864
	ds_read_b128 v[222:225], v175 offset:37888
	ds_read_b128 v[226:229], v175 offset:38912
	ds_read_b128 v[230:233], v175 offset:39936
	global_load_lds_dwordx4 v[240:241], off
	v_lshl_add_u64 v[240:241], s[30:31], 0, v[136:137]
	s_mov_b32 m0, s74
	s_nop 0
	global_load_lds_dwordx4 v[240:241], off
	s_waitcnt vmcnt(8)
	s_waitcnt lgkmcnt(0)
	s_barrier
	s_setprio 1
	s_waitcnt lgkmcnt(0)
	v_mfma_f32_16x16x32_bf16 v[124:127], v[128:131], v[202:205], v[124:127]
	v_mfma_f32_16x16x32_bf16 v[120:123], v[178:181], v[202:205], v[120:123]
	v_mfma_f32_16x16x32_bf16 v[108:111], v[128:131], v[210:213], v[108:111]
	v_mfma_f32_16x16x32_bf16 v[104:107], v[178:181], v[210:213], v[104:107]
	v_mfma_f32_16x16x32_bf16 v[92:95], v[128:131], v[218:221], v[92:95]
	v_mfma_f32_16x16x32_bf16 v[88:91], v[178:181], v[218:221], v[88:91]
	v_mfma_f32_16x16x32_bf16 v[76:79], v[128:131], v[226:229], v[76:79]
	v_mfma_f32_16x16x32_bf16 v[72:75], v[178:181], v[226:229], v[72:75]
	v_mfma_f32_16x16x32_bf16 v[124:127], v[158:161], v[206:209], v[124:127]
	v_mfma_f32_16x16x32_bf16 v[120:123], v[182:185], v[206:209], v[120:123]
	v_mfma_f32_16x16x32_bf16 v[108:111], v[158:161], v[214:217], v[108:111]
	v_mfma_f32_16x16x32_bf16 v[104:107], v[182:185], v[214:217], v[104:107]
	v_mfma_f32_16x16x32_bf16 v[92:95], v[158:161], v[222:225], v[92:95]
	v_mfma_f32_16x16x32_bf16 v[88:91], v[182:185], v[222:225], v[88:91]
	v_mfma_f32_16x16x32_bf16 v[76:79], v[158:161], v[230:233], v[76:79]
	v_mfma_f32_16x16x32_bf16 v[72:75], v[182:185], v[230:233], v[72:75]
	s_setprio 0
	s_setprio 1
	s_cmp_eq_u32 s52, 12
	s_cbranch_scc1 .Lp2_skip2
	v_mfma_f32_16x16x32_bf16 v[116:119], v[186:189], v[202:205], v[116:119]
	v_mfma_f32_16x16x32_bf16 v[112:115], v[194:197], v[202:205], v[112:115]
	v_mfma_f32_16x16x32_bf16 v[100:103], v[186:189], v[210:213], v[100:103]
	v_mfma_f32_16x16x32_bf16 v[96:99], v[194:197], v[210:213], v[96:99]
	v_mfma_f32_16x16x32_bf16 v[84:87], v[186:189], v[218:221], v[84:87]
	v_mfma_f32_16x16x32_bf16 v[80:83], v[194:197], v[218:221], v[80:83]
	v_mfma_f32_16x16x32_bf16 v[68:71], v[186:189], v[226:229], v[68:71]
	v_mfma_f32_16x16x32_bf16 v[64:67], v[194:197], v[226:229], v[64:67]
	v_mfma_f32_16x16x32_bf16 v[116:119], v[190:193], v[206:209], v[116:119]
	v_mfma_f32_16x16x32_bf16 v[112:115], v[198:201], v[206:209], v[112:115]
	v_mfma_f32_16x16x32_bf16 v[100:103], v[190:193], v[214:217], v[100:103]
	v_mfma_f32_16x16x32_bf16 v[96:99], v[198:201], v[214:217], v[96:99]
	v_mfma_f32_16x16x32_bf16 v[84:87], v[190:193], v[222:225], v[84:87]
	v_mfma_f32_16x16x32_bf16 v[80:83], v[198:201], v[222:225], v[80:83]
	v_mfma_f32_16x16x32_bf16 v[68:71], v[190:193], v[230:233], v[68:71]
	v_mfma_f32_16x16x32_bf16 v[64:67], v[198:201], v[230:233], v[64:67]
; #define PG8_STAGE(bufoff, gbase, voff) do { _Pragma("unroll") for (int _i = 0; _i < 2; ++_i) \
;         __builtin_amdgcn_global_load_lds((const unsigned*)((const char*)(gbase) + (voff)[_i]), (LAS unsigned*)(lds + (bufoff) + ldsw + _i * 8192), 16, 0, 0); } while (0)
; #define PG8_LDA(dst, b, h) do { _Pragma("unroll") for (int m = 0; m < 4; ++m) _Pragma("unroll") for (int k = 0; k < 2; ++k) dst[m][k] = *(const LAS bf16x8*)(lds + PG8_SA(b, h) + aoff + m * 2048 + k * 1024); } while (0)
; #define PG8_LDB(dst, b, h) do { _Pragma("unroll") for (int n = 0; n < 2; ++n) _Pragma("unroll") for (int k = 0; k < 2; ++k) dst[n][k] = *(const LAS bf16x8*)(lds + PG8_SB(b, h) + boff + n * 2048 + k * 1024); } while (0)
; #define PG8_MMA(ai, bj, At, Bt) do { __builtin_amdgcn_s_setprio(1); _Pragma("unroll") for (int m = 0; m < 4; ++m) _Pragma("unroll") for (int n = 0; n < 2; ++n) _Pragma("unroll") for (int k = 0; k < 2; ++k) \
;         acc[ai][bj][m][n] = __builtin_amdgcn_mfma_f32_16x16x32_bf16(Bt[n][k], At[m][k], acc[ai][bj][m][n], 0, 0, 0); __builtin_amdgcn_s_setprio(0); } while (0)
; #define PG8_WAIT_V(n) asm volatile("s_waitcnt vmcnt(" #n ")" ::: "memory")
; template <class Epi, class Sched>
; __device__ __forceinline__ void gemm_phase(LAS unsigned char* lds, const Gemm g, const Sched& S, const Epi& E, const int tid) {
;     ...
;             PG8_LDB(B0, 0, 0); PG8_LDB(B1, 0, 1); PG8_SCHED; PG8_LDA(At, 0, 0); PG8_STAGE(PG8_SA(1, 1), a1 + hstepA, voffA);
;             PG8_WAIT_V(8); PG8_WAIT_L(0); PG8_BAR; PG8_MMA(0, 0, At, B0); PG8_MMA(0, 1, At, B1); PG8_BAR; PG8_SCHED;
;             PG8_LDA(At, 0, 1); PG8_STAGE(PG8_SB(0, 0), b2, voffB); PG8_STAGE(PG8_SB(0, 1), b2 + hstepB, voffB); PG8_STAGE(PG8_SA(0, 0), a2, voffA);
;             PG8_WAIT_V(8); PG8_WAIT_L(0); PG8_BAR; PG8_MMA(1, 0, At, B0); PG8_MMA(1, 1, At, B1); PG8_BAR; PG8_SCHED;
;             PG8_LDB(B0, 1, 0); PG8_LDB(B1, 1, 1); PG8_SCHED; PG8_LDA(At, 1, 0); PG8_STAGE(PG8_SA(0, 1), a2 + hstepA, voffA);
;             PG8_WAIT_V(8); PG8_WAIT_L(0); PG8_BAR; PG8_MMA(0, 0, At, B0); PG8_MMA(0, 1, At, B1); PG8_BAR; PG8_SCHED;
;             PG8_LDA(At, 1, 1); PG8_STAGE(PG8_SB(1, 0), b3, voffB); PG8_STAGE(PG8_SB(1, 1), b3 + hstepB, voffB); PG8_STAGE(PG8_SA(1, 0), a3, voffA);
;             PG8_WAIT_V(8); PG8_WAIT_L(0); PG8_BAR; PG8_MMA(1, 0, At, B0); PG8_MMA(1, 1, At, B1); PG8_BAR; PG8_SCHED;
;         }
.Lp2_skip2:
	s_setprio 0
	s_barrier
	s_add_i32 s16, s16, s33
	v_lshl_add_u64 v[162:163], v[162:163], 0, s[78:79]
	s_mov_b32 m0, s16
	ds_read_b128 v[202:205], v175 offset:49152
	ds_read_b128 v[206:209], v175 offset:50176
	ds_read_b128 v[210:213], v175 offset:51200
	ds_read_b128 v[214:217], v175 offset:52224
	ds_read_b128 v[218:221], v175 offset:53248
	ds_read_b128 v[222:225], v175 offset:54272
	ds_read_b128 v[226:229], v175 offset:55296
	ds_read_b128 v[230:233], v175 offset:56320
	global_load_lds_dwordx4 v[162:163], off
	s_add_i32 m0, s16, 0x2000
	s_add_u32 s26, s26, 0x80080
	v_lshl_add_u64 v[162:163], v[234:235], 0, s[78:79]
	s_addc_u32 s27, s27, 0
	s_add_i32 s16, s17, s33
	global_load_lds_dwordx4 v[162:163], off
	v_lshl_add_u64 v[162:163], s[26:27], 0, v[134:135]
	s_mov_b32 m0, s16
	s_nop 0
	global_load_lds_dwordx4 v[162:163], off
	v_lshl_add_u64 v[162:163], s[26:27], 0, v[138:139]
	s_add_i32 m0, s16, 0x2000
	s_nop 0
	global_load_lds_dwordx4 v[162:163], off
	v_lshl_add_u64 v[162:163], v[236:237], 0, s[78:79]
	s_mov_b32 m0, s95
	s_nop 0
	global_load_lds_dwordx4 v[162:163], off
	v_lshl_add_u64 v[162:163], v[238:239], 0, s[78:79]
	s_mov_b32 m0, s0
	s_nop 0
	global_load_lds_dwordx4 v[162:163], off
	s_waitcnt vmcnt(8)
	s_waitcnt lgkmcnt(0)
	s_barrier
	s_setprio 1
	s_waitcnt lgkmcnt(0)
	v_mfma_f32_16x16x32_bf16 v[60:63], v[128:131], v[202:205], v[60:63]
	v_mfma_f32_16x16x32_bf16 v[56:59], v[178:181], v[202:205], v[56:59]
	v_mfma_f32_16x16x32_bf16 v[44:47], v[128:131], v[210:213], v[44:47]
	v_mfma_f32_16x16x32_bf16 v[40:43], v[178:181], v[210:213], v[40:43]
	v_mfma_f32_16x16x32_bf16 v[28:31], v[128:131], v[218:221], v[28:31]
	v_mfma_f32_16x16x32_bf16 v[24:27], v[178:181], v[218:221], v[24:27]
	v_mfma_f32_16x16x32_bf16 v[12:15], v[128:131], v[226:229], v[12:15]
	v_mfma_f32_16x16x32_bf16 v[8:11], v[178:181], v[226:229], v[8:11]
	v_mfma_f32_16x16x32_bf16 v[60:63], v[158:161], v[206:209], v[60:63]
	v_mfma_f32_16x16x32_bf16 v[56:59], v[182:185], v[206:209], v[56:59]
	v_mfma_f32_16x16x32_bf16 v[44:47], v[158:161], v[214:217], v[44:47]
	v_mfma_f32_16x16x32_bf16 v[40:43], v[182:185], v[214:217], v[40:43]
	v_mfma_f32_16x16x32_bf16 v[28:31], v[158:161], v[222:225], v[28:31]
	v_mfma_f32_16x16x32_bf16 v[24:27], v[182:185], v[222:225], v[24:27]
	v_mfma_f32_16x16x32_bf16 v[12:15], v[158:161], v[230:233], v[12:15]
	v_mfma_f32_16x16x32_bf16 v[8:11], v[182:185], v[230:233], v[8:11]
	s_setprio 0
	s_setprio 1
	s_cmp_eq_u32 s52, 12
	s_cbranch_scc1 .Lp2_skip3
	v_mfma_f32_16x16x32_bf16 v[52:55], v[186:189], v[202:205], v[52:55]
	v_mfma_f32_16x16x32_bf16 v[48:51], v[194:197], v[202:205], v[48:51]
	v_mfma_f32_16x16x32_bf16 v[36:39], v[186:189], v[210:213], v[36:39]
	v_mfma_f32_16x16x32_bf16 v[32:35], v[194:197], v[210:213], v[32:35]
	v_mfma_f32_16x16x32_bf16 v[20:23], v[186:189], v[218:221], v[20:23]
	v_mfma_f32_16x16x32_bf16 v[16:19], v[194:197], v[218:221], v[16:19]
	v_mfma_f32_16x16x32_bf16 v[4:7], v[186:189], v[226:229], v[4:7]
	v_mfma_f32_16x16x32_bf16 v[0:3], v[194:197], v[226:229], v[0:3]
	v_mfma_f32_16x16x32_bf16 v[52:55], v[190:193], v[206:209], v[52:55]
	v_mfma_f32_16x16x32_bf16 v[48:51], v[198:201], v[206:209], v[48:51]
	v_mfma_f32_16x16x32_bf16 v[36:39], v[190:193], v[214:217], v[36:39]
	v_mfma_f32_16x16x32_bf16 v[32:35], v[198:201], v[214:217], v[32:35]
	v_mfma_f32_16x16x32_bf16 v[20:23], v[190:193], v[222:225], v[20:23]
	v_mfma_f32_16x16x32_bf16 v[16:19], v[198:201], v[222:225], v[16:19]
	v_mfma_f32_16x16x32_bf16 v[4:7], v[190:193], v[230:233], v[4:7]
	v_mfma_f32_16x16x32_bf16 v[0:3], v[198:201], v[230:233], v[0:3]
.Lp2_skip3:
	s_setprio 0
	s_barrier
	s_add_i32 s48, s48, 2
	s_add_u32 s8, s8, 0x100
	s_addc_u32 s9, s9, 0
	s_add_u32 s38, s38, 0x100
	s_addc_u32 s39, s39, 0
	s_cmp_gt_u32 s48, 29
	s_cbranch_scc0 .LBB0_285
	s_and_b64 vcc, exec, s[90:91]
	s_cbranch_vccz .LBB0_288
	s_barrier
